# strategy 9 (7.12): attention loop's wave-uniform 'max moved' branch tests the first compare's VCC; select moved to the rare rescale path (on top of v022)
# baseline (speedup 1.0000x reference)
; template <int MODE> ...
;     ...
;         if (MODE == 0) {
;             mloc = fmaxf(mloc, __shfl_xor(mloc, 32));
;             const float mnew = mloc > m + 8.0f ? mloc : m;
;             if (__ballot(mnew != m) != 0ull) { const float alpha = __builtin_amdgcn_exp2f(m - mnew); m = mnew; l *= alpha;
; #pragma unroll
;                 for (int dt = 0; dt < 4; ++dt)
; #pragma unroll
;                     for (int i = 0; i < 16; ++i) ot[dt][i] *= alpha; }
.LBB0_2115:
	s_or_b64 exec, exec, s[70:71]
	s_nop 5
	v_mov_b32_e32 v146, v246
	v_add_f32_e32 v148, 0x41000000, v245
	s_nop 0
	v_permlane32_swap_b32_e32 v146, v246
	v_max_f32_e32 v146, v146, v246
	v_cmp_gt_f32_e32 vcc, v146, v148
	s_cbranch_vccz .LBB0_2117
	s_nop 0
	v_cndmask_b32_e32 v146, v245, v146, vcc
	v_sub_f32_e32 v147, v245, v146
	v_exp_f32_e32 v148, v147
	s_nop 0
	v_mul_f32_e32 v243, v243, v148
	v_mul_f32_e32 v80, v80, v148
	v_mul_f32_e32 v81, v81, v148
	v_mul_f32_e32 v78, v78, v148
	v_mul_f32_e32 v79, v79, v148
	v_mul_f32_e32 v76, v76, v148
	v_mul_f32_e32 v77, v77, v148
	v_mul_f32_e32 v74, v74, v148
	v_mul_f32_e32 v75, v75, v148
	v_mul_f32_e32 v72, v72, v148
	v_mul_f32_e32 v73, v73, v148
	v_mul_f32_e32 v70, v70, v148
	v_mul_f32_e32 v71, v71, v148
	v_mul_f32_e32 v68, v68, v148
	v_mul_f32_e32 v69, v69, v148
	v_mul_f32_e32 v66, v66, v148
	v_mul_f32_e32 v67, v67, v148
	v_mul_f32_e32 v64, v64, v148
	v_mul_f32_e32 v65, v65, v148
	v_mul_f32_e32 v62, v62, v148
	v_mul_f32_e32 v63, v63, v148
	v_mul_f32_e32 v60, v60, v148
	v_mul_f32_e32 v61, v61, v148
	v_mul_f32_e32 v58, v58, v148
	v_mul_f32_e32 v59, v59, v148
	v_mul_f32_e32 v56, v56, v148
	v_mul_f32_e32 v57, v57, v148
	v_mul_f32_e32 v54, v54, v148
	v_mul_f32_e32 v55, v55, v148
	v_mul_f32_e32 v52, v52, v148
	v_mul_f32_e32 v53, v53, v148
	v_mul_f32_e32 v50, v50, v148
	v_mul_f32_e32 v51, v51, v148
	v_mul_f32_e32 v48, v48, v148
	v_mul_f32_e32 v49, v49, v148
	v_mul_f32_e32 v46, v46, v148
	v_mul_f32_e32 v47, v47, v148
	v_mul_f32_e32 v44, v44, v148
	v_mul_f32_e32 v45, v45, v148
	v_mul_f32_e32 v42, v42, v148
	v_mul_f32_e32 v43, v43, v148
	v_mul_f32_e32 v40, v40, v148
	v_mul_f32_e32 v41, v41, v148
	v_mul_f32_e32 v38, v38, v148
	v_mul_f32_e32 v39, v39, v148
	v_mul_f32_e32 v36, v36, v148
	v_mul_f32_e32 v37, v37, v148
	v_mul_f32_e32 v34, v34, v148
	v_mul_f32_e32 v35, v35, v148
	v_mul_f32_e32 v32, v32, v148
	v_mul_f32_e32 v33, v33, v148
	v_mul_f32_e32 v30, v30, v148
	v_mul_f32_e32 v31, v31, v148
	v_mul_f32_e32 v28, v28, v148
	v_mul_f32_e32 v29, v29, v148
	v_mul_f32_e32 v26, v26, v148
	v_mul_f32_e32 v27, v27, v148
	v_mul_f32_e32 v24, v24, v148
	v_mul_f32_e32 v25, v25, v148
	v_mul_f32_e32 v22, v22, v148
	v_mul_f32_e32 v23, v23, v148
	v_mul_f32_e32 v20, v20, v148
	v_mul_f32_e32 v21, v21, v148
	v_mul_f32_e32 v18, v18, v148
	v_mul_f32_e32 v19, v19, v148
	s_branch .LBB0_2118
